# pvprio_s + nt hint on the 32 final f32 output stores (written once, never re-read)
# baseline (speedup 1.0000x reference)
; #define GAS __attribute__((address_space(1)))
;     __device__ __forceinline__ void operator()(f32x4 (&acc)[2][2][4][2], const Unit& u, int ui, int wr, int wc, int fr, int fq) const {
;     ...
;         f32x4 g0[2], g1[2];
; #pragma unroll
;         for (int bj = 0; bj < 2; ++bj) { g0[bj] = *(const GAS f32x4*)((const GAS float*)gfin + col0 + bj * HALF); g1[bj] = *(const GAS f32x4*)((const GAS float*)gfin + col0 + bj * HALF + 4); }
;         GAS float* op = (GAS float*)out + (size_t)(u.pm * BM + row0) * D + col0;
; #pragma unroll
;         for (int ai = 0; ai < 2; ++ai)
; #pragma unroll
;             for (int m = 0; m < 4; ++m) { const float iv = S[ai * HALF + row0 + m * 16];
; #pragma unroll
;                 for (int bj = 0; bj < 2; ++bj) { *(GAS f32x4*)(op + bj * HALF) = acc[ai][bj][m][0] * iv * g0[bj]; *(GAS f32x4*)(op + bj * HALF + 4) = acc[ai][bj][m][1] * iv * g1[bj]; }
;                 const int adv = (m == 3) ? (HALF - 48) : 16; op += (size_t)adv * D; asm volatile("" : "+v"(op)); }
.LBB0_778:
	s_or_b64 exec, exec, s[18:19]
	v_readlane_b32 s40, v252, 5
	v_lshlrev_b64 v[134:135], 2, v[192:193]
	v_readlane_b32 s50, v252, 15
	v_readlane_b32 s51, v252, 16
	s_waitcnt vmcnt(0) lgkmcnt(0)
	s_barrier
	v_lshl_add_u32 v136, v194, 2, 0
	v_lshl_add_u64 v[2:3], s[50:51], 0, v[134:135]
	global_load_dwordx4 v[14:17], v[2:3], off
	global_load_dwordx4 v[10:13], v[2:3], off offset:16
	global_load_dwordx4 v[6:9], v[2:3], off offset:512
	s_nop 0
	global_load_dwordx4 v[2:5], v[2:3], off offset:528
	v_add_u32_e32 v158, 0x21400, v136
	ds_read_b32 v136, v158
	v_ashrrev_i32_e32 v191, 31, v190
	v_readlane_b32 s52, v252, 17
	v_readlane_b32 s53, v252, 18
	v_lshlrev_b64 v[138:139], 12, v[190:191]
	s_mov_b64 s[14:15], 0x10000
	v_lshl_add_u64 v[138:139], s[52:53], 0, v[138:139]
	v_lshl_add_u64 v[150:151], v[138:139], 0, v[134:135]
	s_waitcnt lgkmcnt(0)
	v_pk_mul_f32 v[134:135], v[162:163], v[136:137] op_sel_hi:[1,0]
	v_pk_mul_f32 v[138:139], v[164:165], v[136:137] op_sel_hi:[1,0]
	v_lshl_add_u64 v[152:153], v[150:151], 0, s[14:15]
	v_pk_mul_f32 v[140:141], v[154:155], v[136:137] op_sel_hi:[1,0]
	v_pk_mul_f32 v[142:143], v[156:157], v[136:137] op_sel_hi:[1,0]
	v_pk_mul_f32 v[144:145], v[146:147], v[136:137] op_sel_hi:[1,0]
	v_pk_mul_f32 v[146:147], v[148:149], v[136:137] op_sel_hi:[1,0]
	v_pk_mul_f32 v[148:149], v[130:131], v[136:137] op_sel_hi:[1,0]
	v_pk_mul_f32 v[154:155], v[132:133], v[136:137] op_sel_hi:[1,0]
	s_mov_b64 s[18:19], 0x50000
	s_and_b64 vcc, exec, s[36:37]
	v_readlane_b32 s41, v252, 6
	v_readlane_b32 s42, v252, 7
	v_readlane_b32 s43, v252, 8
	v_readlane_b32 s44, v252, 9
	v_readlane_b32 s45, v252, 10
	v_readlane_b32 s46, v252, 11
	v_readlane_b32 s47, v252, 12
	v_readlane_b32 s48, v252, 13
	v_readlane_b32 s49, v252, 14
	v_readlane_b32 s54, v252, 19
	v_readlane_b32 s55, v252, 20
	s_waitcnt vmcnt(3)
	v_pk_mul_f32 v[132:133], v[16:17], v[138:139]
	v_pk_mul_f32 v[130:131], v[14:15], v[134:135]
	s_waitcnt vmcnt(2)
	v_pk_mul_f32 v[136:137], v[12:13], v[142:143]
	v_pk_mul_f32 v[134:135], v[10:11], v[140:141]
	s_waitcnt vmcnt(1)
	v_pk_mul_f32 v[140:141], v[8:9], v[146:147]
	v_pk_mul_f32 v[138:139], v[6:7], v[144:145]
	s_waitcnt vmcnt(0)
	v_pk_mul_f32 v[144:145], v[4:5], v[154:155]
	v_pk_mul_f32 v[142:143], v[2:3], v[148:149]
	global_store_dwordx4 v[150:151], v[130:133], off nt
	global_store_dwordx4 v[150:151], v[134:137], off offset:16 nt
	global_store_dwordx4 v[150:151], v[138:141], off offset:512 nt
	global_store_dwordx4 v[150:151], v[142:145], off offset:528 nt
	ds_read_b32 v130, v158 offset:64
	v_lshl_add_u64 v[132:133], v[152:153], 0, s[14:15]
	s_waitcnt lgkmcnt(0)
	v_pk_mul_f32 v[118:119], v[118:119], v[130:131] op_sel_hi:[1,0]
	v_pk_mul_f32 v[120:121], v[120:121], v[130:131] op_sel_hi:[1,0]
	v_pk_mul_f32 v[110:111], v[110:111], v[130:131] op_sel_hi:[1,0]
	v_pk_mul_f32 v[112:113], v[112:113], v[130:131] op_sel_hi:[1,0]
	v_pk_mul_f32 v[134:135], v[106:107], v[130:131] op_sel_hi:[1,0]
	v_pk_mul_f32 v[136:137], v[108:109], v[130:131] op_sel_hi:[1,0]
	v_pk_mul_f32 v[138:139], v[102:103], v[130:131] op_sel_hi:[1,0]
	v_pk_mul_f32 v[130:131], v[104:105], v[130:131] op_sel_hi:[1,0]
	v_pk_mul_f32 v[104:105], v[16:17], v[120:121]
	v_pk_mul_f32 v[102:103], v[14:15], v[118:119]
	v_pk_mul_f32 v[108:109], v[12:13], v[112:113]
	v_pk_mul_f32 v[106:107], v[10:11], v[110:111]
	v_pk_mul_f32 v[112:113], v[8:9], v[136:137]
	v_pk_mul_f32 v[110:111], v[6:7], v[134:135]
	v_pk_mul_f32 v[120:121], v[4:5], v[130:131]
	v_pk_mul_f32 v[118:119], v[2:3], v[138:139]
	global_store_dwordx4 v[152:153], v[102:105], off nt
	global_store_dwordx4 v[152:153], v[106:109], off offset:16 nt
	global_store_dwordx4 v[152:153], v[110:113], off offset:512 nt
	global_store_dwordx4 v[152:153], v[118:121], off offset:528 nt
	ds_read_b32 v102, v158 offset:128
	v_lshl_add_u64 v[104:105], v[132:133], 0, s[14:15]
	s_waitcnt lgkmcnt(0)
	v_pk_mul_f32 v[94:95], v[94:95], v[102:103] op_sel_hi:[1,0]
	v_pk_mul_f32 v[96:97], v[96:97], v[102:103] op_sel_hi:[1,0]
	v_pk_mul_f32 v[90:91], v[90:91], v[102:103] op_sel_hi:[1,0]
	v_pk_mul_f32 v[92:93], v[92:93], v[102:103] op_sel_hi:[1,0]
	v_pk_mul_f32 v[106:107], v[86:87], v[102:103] op_sel_hi:[1,0]
	v_pk_mul_f32 v[108:109], v[88:89], v[102:103] op_sel_hi:[1,0]
	v_pk_mul_f32 v[110:111], v[82:83], v[102:103] op_sel_hi:[1,0]
	v_pk_mul_f32 v[102:103], v[84:85], v[102:103] op_sel_hi:[1,0]
	v_pk_mul_f32 v[84:85], v[16:17], v[96:97]
	v_pk_mul_f32 v[82:83], v[14:15], v[94:95]
	v_pk_mul_f32 v[88:89], v[12:13], v[92:93]
	v_pk_mul_f32 v[86:87], v[10:11], v[90:91]
	v_pk_mul_f32 v[92:93], v[8:9], v[108:109]
	v_pk_mul_f32 v[90:91], v[6:7], v[106:107]
	v_pk_mul_f32 v[96:97], v[4:5], v[102:103]
	v_pk_mul_f32 v[94:95], v[2:3], v[110:111]
	global_store_dwordx4 v[132:133], v[82:85], off nt
	global_store_dwordx4 v[132:133], v[86:89], off offset:16 nt
	global_store_dwordx4 v[132:133], v[90:93], off offset:512 nt
	global_store_dwordx4 v[132:133], v[94:97], off offset:528 nt
	ds_read_b32 v82, v158 offset:192
	s_waitcnt lgkmcnt(0)
; #define GAS __attribute__((address_space(1)))
;     __device__ __forceinline__ void operator()(f32x4 (&acc)[2][2][4][2], const Unit& u, int ui, int wr, int wc, int fr, int fq) const {
;     ...
; #pragma unroll
;         for (int ai = 0; ai < 2; ++ai)
; #pragma unroll
;             for (int m = 0; m < 4; ++m) { const float iv = S[ai * HALF + row0 + m * 16];
; #pragma unroll
;                 for (int bj = 0; bj < 2; ++bj) { *(GAS f32x4*)(op + bj * HALF) = acc[ai][bj][m][0] * iv * g0[bj]; *(GAS f32x4*)(op + bj * HALF + 4) = acc[ai][bj][m][1] * iv * g1[bj]; }
;                 const int adv = (m == 3) ? (HALF - 48) : 16; op += (size_t)adv * D; asm volatile("" : "+v"(op)); }
;         asm volatile("s_waitcnt lgkmcnt(0)" ::: "memory"); __builtin_amdgcn_s_barrier(); asm volatile("" ::: "memory");
	v_pk_mul_f32 v[78:79], v[78:79], v[82:83] op_sel_hi:[1,0]
	v_pk_mul_f32 v[80:81], v[80:81], v[82:83] op_sel_hi:[1,0]
	v_pk_mul_f32 v[74:75], v[74:75], v[82:83] op_sel_hi:[1,0]
	v_pk_mul_f32 v[76:77], v[76:77], v[82:83] op_sel_hi:[1,0]
	v_pk_mul_f32 v[84:85], v[70:71], v[82:83] op_sel_hi:[1,0]
	v_pk_mul_f32 v[86:87], v[72:73], v[82:83] op_sel_hi:[1,0]
	v_pk_mul_f32 v[88:89], v[66:67], v[82:83] op_sel_hi:[1,0]
	v_pk_mul_f32 v[82:83], v[68:69], v[82:83] op_sel_hi:[1,0]
	v_pk_mul_f32 v[68:69], v[16:17], v[80:81]
	v_pk_mul_f32 v[66:67], v[14:15], v[78:79]
	v_pk_mul_f32 v[72:73], v[12:13], v[76:77]
	v_pk_mul_f32 v[70:71], v[10:11], v[74:75]
	v_pk_mul_f32 v[76:77], v[8:9], v[86:87]
	v_pk_mul_f32 v[74:75], v[6:7], v[84:85]
	v_pk_mul_f32 v[80:81], v[4:5], v[82:83]
	v_pk_mul_f32 v[78:79], v[2:3], v[88:89]
	global_store_dwordx4 v[104:105], v[66:69], off nt
	global_store_dwordx4 v[104:105], v[70:73], off offset:16 nt
	global_store_dwordx4 v[104:105], v[74:77], off offset:512 nt
	global_store_dwordx4 v[104:105], v[78:81], off offset:528 nt
	v_lshl_add_u64 v[66:67], v[104:105], 0, s[18:19]
	ds_read_b32 v68, v158 offset:512
	s_waitcnt lgkmcnt(0)
	v_pk_mul_f32 v[50:51], v[50:51], v[68:69] op_sel_hi:[1,0]
	v_pk_mul_f32 v[52:53], v[52:53], v[68:69] op_sel_hi:[1,0]
	v_pk_mul_f32 v[62:63], v[62:63], v[68:69] op_sel_hi:[1,0]
	v_pk_mul_f32 v[64:65], v[64:65], v[68:69] op_sel_hi:[1,0]
	v_pk_mul_f32 v[58:59], v[58:59], v[68:69] op_sel_hi:[1,0]
	v_pk_mul_f32 v[60:61], v[60:61], v[68:69] op_sel_hi:[1,0]
	v_pk_mul_f32 v[54:55], v[54:55], v[68:69] op_sel_hi:[1,0]
	v_pk_mul_f32 v[56:57], v[56:57], v[68:69] op_sel_hi:[1,0]
	v_pk_mul_f32 v[52:53], v[4:5], v[52:53]
	v_pk_mul_f32 v[50:51], v[2:3], v[50:51]
	v_pk_mul_f32 v[64:65], v[16:17], v[64:65]
	v_pk_mul_f32 v[62:63], v[14:15], v[62:63]
	v_pk_mul_f32 v[60:61], v[12:13], v[60:61]
	v_pk_mul_f32 v[58:59], v[10:11], v[58:59]
	v_pk_mul_f32 v[56:57], v[8:9], v[56:57]
	v_pk_mul_f32 v[54:55], v[6:7], v[54:55]
	global_store_dwordx4 v[66:67], v[50:53], off offset:528 nt
	global_store_dwordx4 v[66:67], v[62:65], off nt
	global_store_dwordx4 v[66:67], v[58:61], off offset:16 nt
	v_lshl_add_u64 v[50:51], v[66:67], 0, s[14:15]
	global_store_dwordx4 v[66:67], v[54:57], off offset:512 nt
	ds_read_b32 v52, v158 offset:576
	s_waitcnt lgkmcnt(0)
	v_pk_mul_f32 v[34:35], v[34:35], v[52:53] op_sel_hi:[1,0]
	v_pk_mul_f32 v[36:37], v[36:37], v[52:53] op_sel_hi:[1,0]
	v_pk_mul_f32 v[46:47], v[46:47], v[52:53] op_sel_hi:[1,0]
	v_pk_mul_f32 v[48:49], v[48:49], v[52:53] op_sel_hi:[1,0]
	v_pk_mul_f32 v[42:43], v[42:43], v[52:53] op_sel_hi:[1,0]
	v_pk_mul_f32 v[44:45], v[44:45], v[52:53] op_sel_hi:[1,0]
	v_pk_mul_f32 v[38:39], v[38:39], v[52:53] op_sel_hi:[1,0]
	v_pk_mul_f32 v[40:41], v[40:41], v[52:53] op_sel_hi:[1,0]
	v_pk_mul_f32 v[36:37], v[4:5], v[36:37]
	v_pk_mul_f32 v[34:35], v[2:3], v[34:35]
	v_pk_mul_f32 v[48:49], v[16:17], v[48:49]
	v_pk_mul_f32 v[46:47], v[14:15], v[46:47]
	v_pk_mul_f32 v[44:45], v[12:13], v[44:45]
	v_pk_mul_f32 v[42:43], v[10:11], v[42:43]
	v_pk_mul_f32 v[40:41], v[8:9], v[40:41]
	v_pk_mul_f32 v[38:39], v[6:7], v[38:39]
	global_store_dwordx4 v[50:51], v[34:37], off offset:528 nt
	global_store_dwordx4 v[50:51], v[46:49], off nt
	global_store_dwordx4 v[50:51], v[42:45], off offset:16 nt
	v_lshl_add_u64 v[34:35], v[50:51], 0, s[14:15]
	global_store_dwordx4 v[50:51], v[38:41], off offset:512 nt
	ds_read_b32 v36, v158 offset:640
	s_waitcnt lgkmcnt(0)
	v_pk_mul_f32 v[18:19], v[18:19], v[36:37] op_sel_hi:[1,0]
	v_pk_mul_f32 v[20:21], v[20:21], v[36:37] op_sel_hi:[1,0]
	v_pk_mul_f32 v[30:31], v[30:31], v[36:37] op_sel_hi:[1,0]
	v_pk_mul_f32 v[32:33], v[32:33], v[36:37] op_sel_hi:[1,0]
	v_pk_mul_f32 v[26:27], v[26:27], v[36:37] op_sel_hi:[1,0]
	v_pk_mul_f32 v[28:29], v[28:29], v[36:37] op_sel_hi:[1,0]
	v_pk_mul_f32 v[22:23], v[22:23], v[36:37] op_sel_hi:[1,0]
	v_pk_mul_f32 v[24:25], v[24:25], v[36:37] op_sel_hi:[1,0]
	v_pk_mul_f32 v[20:21], v[4:5], v[20:21]
	v_pk_mul_f32 v[18:19], v[2:3], v[18:19]
	v_pk_mul_f32 v[32:33], v[16:17], v[32:33]
	v_pk_mul_f32 v[30:31], v[14:15], v[30:31]
	v_pk_mul_f32 v[28:29], v[12:13], v[28:29]
	v_pk_mul_f32 v[26:27], v[10:11], v[26:27]
	v_pk_mul_f32 v[24:25], v[8:9], v[24:25]
	v_pk_mul_f32 v[22:23], v[6:7], v[22:23]
	global_store_dwordx4 v[34:35], v[18:21], off offset:528 nt
	global_store_dwordx4 v[34:35], v[30:33], off nt
	global_store_dwordx4 v[34:35], v[26:29], off offset:16 nt
	v_lshl_add_u64 v[18:19], v[34:35], 0, s[14:15]
	global_store_dwordx4 v[34:35], v[22:25], off offset:512 nt
	ds_read_b32 v20, v158 offset:704
	s_waitcnt lgkmcnt(0)
	v_pk_mul_f32 v[22:23], v[122:123], v[20:21] op_sel_hi:[1,0]
	v_pk_mul_f32 v[24:25], v[114:115], v[20:21] op_sel_hi:[1,0]
	v_pk_mul_f32 v[14:15], v[14:15], v[22:23]
	v_pk_mul_f32 v[16:17], v[16:17], v[24:25]
	global_store_dwordx4 v[18:19], v[14:17], off nt
	s_nop 1
	v_pk_mul_f32 v[14:15], v[124:125], v[20:21] op_sel_hi:[1,0]
	v_pk_mul_f32 v[16:17], v[116:117], v[20:21] op_sel_hi:[1,0]
	v_pk_mul_f32 v[10:11], v[10:11], v[14:15]
	v_pk_mul_f32 v[12:13], v[12:13], v[16:17]
	global_store_dwordx4 v[18:19], v[10:13], off offset:16 nt
	s_nop 1
	v_pk_mul_f32 v[10:11], v[126:127], v[20:21] op_sel_hi:[1,0]
	v_pk_mul_f32 v[12:13], v[98:99], v[20:21] op_sel_hi:[1,0]
	v_pk_mul_f32 v[6:7], v[6:7], v[10:11]
	v_pk_mul_f32 v[8:9], v[8:9], v[12:13]
	global_store_dwordx4 v[18:19], v[6:9], off offset:512 nt
	s_nop 1
	v_pk_mul_f32 v[6:7], v[128:129], v[20:21] op_sel_hi:[1,0]
	v_pk_mul_f32 v[8:9], v[100:101], v[20:21] op_sel_hi:[1,0]
	v_pk_mul_f32 v[2:3], v[2:3], v[6:7]
	v_pk_mul_f32 v[4:5], v[4:5], v[8:9]
	global_store_dwordx4 v[18:19], v[2:5], off offset:528 nt
	s_nop 1
	v_lshl_add_u64 v[2:3], v[18:19], 0, s[18:19]
	s_waitcnt lgkmcnt(0)
	s_barrier
	s_mov_b64 s[18:19], -1
	s_cbranch_vccnz .LBB0_720
	s_andn2_b64 vcc, exec, s[16:17]
	s_cbranch_vccnz .LBB0_719
	s_barrier
	s_branch .LBB0_719
